# P0 xn rmsnorm loop software-pipelined: next iteration's 16 loads issued before processing current (second register set)
# baseline (speedup 1.0000x reference)
.LBB0_52:
	s_or_b64 exec, exec, s[6:7]
	s_load_dwordx16 s[4:19], s[0:1], 0x0
	s_movk_i32 s0, 0x4080
	v_lshlrev_b32_e32 v164, 2, v165
	v_mov_b32_e32 v83, 0
	v_cmp_gt_i32_e32 vcc, s0, v91
	s_waitcnt lgkmcnt(0)
	v_writelane_b32 v252, s4, 1
	v_lshlrev_b32_e32 v162, 3, v165
	v_mbcnt_lo_u32_b32 v204, -1, 0
	v_writelane_b32 v252, s5, 2
	v_writelane_b32 v252, s6, 3
	v_writelane_b32 v252, s7, 4
	v_writelane_b32 v252, s8, 5
	v_writelane_b32 v252, s9, 6
	v_writelane_b32 v252, s10, 7
	v_writelane_b32 v252, s11, 8
	v_writelane_b32 v252, s12, 9
	v_writelane_b32 v252, s13, 10
	v_writelane_b32 v252, s14, 11
	v_writelane_b32 v252, s15, 12
	v_writelane_b32 v252, s16, 13
	v_writelane_b32 v252, s17, 14
	v_writelane_b32 v252, s18, 15
	v_writelane_b32 v252, s19, 16
	s_and_saveexec_b64 s[12:13], vcc
	s_cbranch_execz .LBB0_75
	v_lshlrev_b32_e32 v82, 2, v164
	global_load_dwordx4 v[2:5], v82, s[56:57]
	global_load_dwordx4 v[6:9], v82, s[56:57] offset:1024
	global_load_dwordx4 v[10:13], v82, s[56:57] offset:2048
	global_load_dwordx4 v[14:17], v82, s[56:57] offset:3072
	s_add_u32 s8, s80, 0x1908800
	s_addc_u32 s9, s81, 0
	v_and_b32_e32 v20, 1, v0
	v_and_b32_e32 v18, 0x1f0, v205
	v_mov_b32_e32 v19, v83
	v_cmp_eq_u32_e64 s[4:5], 0, v20
	v_lshl_add_u64 v[18:19], s[8:9], 0, v[18:19]
	v_lshlrev_b32_e32 v20, 9, v20
	v_mov_b32_e32 v21, v83
	v_lshl_add_u64 v[86:87], v[18:19], 0, v[20:21]
	v_lshlrev_b32_e32 v18, 2, v32
	v_mbcnt_hi_u32_b32 v94, -1, v204
	s_add_u32 s16, s80, 0xc3000
	v_mov_b32_e32 v163, v83
	v_lshl_or_b32 v88, s2, 5, v18
	v_and_b32_e32 v18, 64, v94
	s_mov_b32 s14, 0
	v_cmp_eq_u32_e64 s[0:1], 0, v165
	v_cmp_ne_u32_e64 s[6:7], 0, v165
	s_addc_u32 s17, s81, 0
	v_lshl_add_u64 v[84:85], s[8:9], 0, v[162:163]
	s_lshl_b32 s3, s82, 5
	s_mov_b64 s[18:19], 0
	s_movk_i32 s22, 0x4044
	s_movk_i32 s23, 0x3fff
	s_movk_i32 s24, 0x403f
	v_mov_b32_e32 v92, 0x358637bd
	s_mov_b32 s25, 0xf800000
	v_mov_b32_e32 v93, 0x260
	s_mov_b32 s26, 0x800000
	s_movk_i32 s27, 0x407f
	v_add_u32_e32 v95, 64, v18
	v_xor_b32_e32 v96, 1, v94
	v_xor_b32_e32 v97, 2, v94
	v_xor_b32_e32 v98, 4, v94
	v_xor_b32_e32 v99, 8, v94
	v_xor_b32_e32 v100, 16, v94
	s_cmpk_lg_u32 s82, 0x100
	s_cbranch_scc1 .Lxn_slow
	v_readlane_b32 s36, v252, 1
	v_readlane_b32 s37, v252, 2
	v_ashrrev_i32_e32 v89, 31, v88
	s_mov_b32 s100, 0x2000000
	s_mov_b32 s101, 0
	v_lshlrev_b64 v[226:227], 12, v[88:89]
	v_lshl_add_u64 v[226:227], v[226:227], 0, s[36:37]
	v_lshl_add_u64 v[226:227], v[226:227], 0, v[82:83]
	s_movk_i32 s36, 0x1000
	s_mov_b32 s37, 0
	v_lshl_add_u64 v[228:229], v[226:227], 0, s[36:37]
	v_lshl_add_u64 v[230:231], v[228:229], 0, s[36:37]
	v_lshl_add_u64 v[232:233], v[230:231], 0, s[36:37]
	global_load_dwordx4 v[222:225], v[226:227], off
	global_load_dwordx4 v[218:221], v[226:227], off offset:1024
	global_load_dwordx4 v[210:213], v[226:227], off offset:3072
	global_load_dwordx4 v[214:217], v[226:227], off offset:2048
	global_load_dwordx4 v[206:209], v[228:229], off
	global_load_dwordx4 v[158:161], v[228:229], off offset:1024
	global_load_dwordx4 v[154:157], v[228:229], off offset:2048
	global_load_dwordx4 v[150:153], v[228:229], off offset:3072
	global_load_dwordx4 v[146:149], v[230:231], off
	global_load_dwordx4 v[142:145], v[230:231], off offset:1024
	global_load_dwordx4 v[138:141], v[230:231], off offset:2048
	global_load_dwordx4 v[134:137], v[230:231], off offset:3072
	global_load_dwordx4 v[130:133], v[232:233], off
	global_load_dwordx4 v[126:129], v[232:233], off offset:1024
	global_load_dwordx4 v[122:125], v[232:233], off offset:2048
	global_load_dwordx4 v[118:121], v[232:233], off offset:3072
	s_mov_b32 s99, 0
	s_waitcnt vmcnt(0)
	s_branch .Lxn_fcopy
.Lxn_floop:
	s_waitcnt vmcnt(8)
.Lxn_fcopy:
	v_mov_b64_e32 v[80:81], v[224:225]
	v_mov_b64_e32 v[78:79], v[222:223]
	v_mov_b64_e32 v[76:77], v[220:221]
	v_mov_b64_e32 v[74:75], v[218:219]
	v_mov_b64_e32 v[72:73], v[216:217]
	v_mov_b64_e32 v[70:71], v[214:215]
	v_mov_b64_e32 v[68:69], v[212:213]
	v_mov_b64_e32 v[66:67], v[210:211]
	v_mov_b64_e32 v[64:65], v[208:209]
	v_mov_b64_e32 v[62:63], v[206:207]
	v_mov_b64_e32 v[60:61], v[160:161]
	v_mov_b64_e32 v[58:59], v[158:159]
	v_mov_b64_e32 v[56:57], v[156:157]
	v_mov_b64_e32 v[54:55], v[154:155]
	v_mov_b64_e32 v[52:53], v[152:153]
	v_mov_b64_e32 v[50:51], v[150:151]
	v_mov_b64_e32 v[48:49], v[148:149]
	v_mov_b64_e32 v[46:47], v[146:147]
	v_mov_b64_e32 v[44:45], v[144:145]
	v_mov_b64_e32 v[42:43], v[142:143]
	v_mov_b64_e32 v[40:41], v[140:141]
	v_mov_b64_e32 v[38:39], v[138:139]
	v_mov_b64_e32 v[36:37], v[136:137]
	v_mov_b64_e32 v[34:35], v[134:135]
	v_mov_b64_e32 v[32:33], v[132:133]
	v_mov_b64_e32 v[30:31], v[130:131]
	v_mov_b64_e32 v[28:29], v[128:129]
	v_mov_b64_e32 v[26:27], v[126:127]
	v_mov_b64_e32 v[24:25], v[124:125]
	v_mov_b64_e32 v[22:23], v[122:123]
	v_mov_b64_e32 v[20:21], v[120:121]
	v_mov_b64_e32 v[18:19], v[118:119]
	s_cmp_eq_u32 s99, 7
	s_cbranch_scc1 .Lxn_fnoload
	v_lshl_add_u64 v[226:227], v[226:227], 0, s[100:101]
	v_lshl_add_u64 v[228:229], v[228:229], 0, s[100:101]
	v_lshl_add_u64 v[230:231], v[230:231], 0, s[100:101]
	v_lshl_add_u64 v[232:233], v[232:233], 0, s[100:101]
	global_load_dwordx4 v[222:225], v[226:227], off
	global_load_dwordx4 v[218:221], v[226:227], off offset:1024
	global_load_dwordx4 v[210:213], v[226:227], off offset:3072
	global_load_dwordx4 v[214:217], v[226:227], off offset:2048
	global_load_dwordx4 v[206:209], v[228:229], off
	global_load_dwordx4 v[158:161], v[228:229], off offset:1024
	global_load_dwordx4 v[154:157], v[228:229], off offset:2048
	global_load_dwordx4 v[150:153], v[228:229], off offset:3072
	global_load_dwordx4 v[146:149], v[230:231], off
	global_load_dwordx4 v[142:145], v[230:231], off offset:1024
	global_load_dwordx4 v[138:141], v[230:231], off offset:2048
	global_load_dwordx4 v[134:137], v[230:231], off offset:3072
	global_load_dwordx4 v[130:133], v[232:233], off
	global_load_dwordx4 v[126:129], v[232:233], off offset:1024
	global_load_dwordx4 v[122:125], v[232:233], off offset:2048
	global_load_dwordx4 v[118:121], v[232:233], off offset:3072
.Lxn_fnoload:
	v_ashrrev_i32_e32 v89, 31, v88
	v_pk_mul_f32 v[102:103], v[80:81], v[80:81]
	v_cmp_lt_i32_e32 vcc, v96, v95
	v_pk_mul_f32 v[104:105], v[78:79], v[78:79]
	v_pk_mul_f32 v[106:107], v[76:77], v[76:77]
	v_pk_mul_f32 v[108:109], v[74:75], v[74:75]
	v_cndmask_b32_e32 v90, v94, v96, vcc
	v_pk_mov_b32 v[112:113], v[104:105], v[102:103] op_sel:[1,0]
	v_mov_b32_e32 v105, v103
	v_pk_mov_b32 v[102:103], v[108:109], v[106:107] op_sel:[1,0]
	v_mov_b32_e32 v109, v107
	v_lshlrev_b32_e32 v101, 2, v90
	v_mul_f32_e32 v90, v71, v71
	v_mul_f32_e32 v110, v73, v73
	v_pk_add_f32 v[104:105], v[112:113], v[104:105]
	v_pk_add_f32 v[102:103], v[102:103], v[108:109]
	v_mul_f32_e32 v114, v66, v66
	v_mul_f32_e32 v115, v67, v67
	v_mul_f32_e32 v116, v68, v68
	v_mul_f32_e32 v117, v69, v69
	v_pk_fma_f32 v[106:107], v[70:71], v[70:71], v[90:91] op_sel_hi:[1,1,0]
	v_pk_fma_f32 v[110:111], v[72:73], v[72:73], v[110:111] op_sel_hi:[1,1,0]
	v_pk_add_f32 v[104:105], v[104:105], v[104:105] op_sel:[0,1] op_sel_hi:[1,0]
	v_pk_add_f32 v[102:103], v[102:103], v[102:103] op_sel:[0,1] op_sel_hi:[1,0]
	v_mov_b32_e32 v107, v116
	v_mov_b32_e32 v111, v117
	v_mov_b32_e32 v105, v114
	v_mov_b32_e32 v103, v115
	v_pk_add_f32 v[102:103], v[104:105], v[102:103]
	v_pk_add_f32 v[104:105], v[106:107], v[110:111]
	v_cmp_lt_i32_e32 vcc, v97, v95
	v_pk_add_f32 v[102:103], v[102:103], v[104:105]
	s_nop 0
	v_add_f32_e32 v102, v102, v103
	s_nop 1
	v_add_f32_dpp v102, v102, v102 quad_perm:[1,0,3,2] row_mask:0xf bank_mask:0xf
	s_nop 1
	v_add_f32_dpp v102, v102, v102 quad_perm:[2,3,0,1] row_mask:0xf bank_mask:0xf
	s_nop 1
	v_add_f32_dpp v102, v102, v102 row_half_mirror row_mask:0xf bank_mask:0xf
	s_nop 1
	v_add_f32_dpp v102, v102, v102 row_mirror row_mask:0xf bank_mask:0xf
	s_nop 1
	v_add_f32_dpp v102, v102, v102 row_bcast:15 row_mask:0xa bank_mask:0xf
	s_nop 1
	v_add_f32_dpp v102, v102, v102 row_bcast:31 row_mask:0xc bank_mask:0xf
	s_nop 0
	v_readlane_b32 s98, v102, 63
	s_nop 1
	v_mov_b32_e32 v102, s98
	v_fmamk_f32 v102, v102, 0x3a800000, v92
	s_and_saveexec_b64 s[10:11], s[0:1]
	s_cbranch_execz .Lxn_f66
	v_mul_f32_e32 v107, 0x4f800000, v102
	v_cmp_gt_f32_e32 vcc, s25, v102
	s_nop 1
	v_cndmask_b32_e32 v107, v102, v107, vcc
	v_sqrt_f32_e32 v108, v107
	s_nop 0
	v_add_u32_e32 v109, -1, v108
	v_fma_f32 v111, -v109, v108, v107
	v_add_u32_e32 v110, 1, v108
	v_cmp_ge_f32_e64 s[8:9], 0, v111
	s_nop 1
	v_cndmask_b32_e64 v109, v108, v109, s[8:9]
	v_fma_f32 v108, -v110, v108, v107
	v_cmp_lt_f32_e64 s[8:9], 0, v108
	s_nop 1
	v_cndmask_b32_e64 v108, v109, v110, s[8:9]
	v_mul_f32_e32 v109, 0x37800000, v108
	v_cndmask_b32_e32 v108, v108, v109, vcc
	v_cmp_class_f32_e32 vcc, v107, v93
	s_nop 1
	v_cndmask_b32_e32 v107, v108, v107, vcc
	v_lshl_add_u64 v[108:109], v[88:89], 2, s[16:17]
	global_store_dword v[108:109], v107, off
.Lxn_f66:
	s_or_b64 exec, exec, s[10:11]
	v_pk_mul_f32 v[108:109], v[64:65], v[64:65]
	v_pk_mul_f32 v[110:111], v[62:63], v[62:63]
	v_mul_f32_e32 v107, v50, v50
	v_pk_mov_b32 v[112:113], v[110:111], v[108:109] op_sel:[1,0]
	v_mov_b32_e32 v111, v109
	v_pk_add_f32 v[108:109], v[112:113], v[110:111]
	v_pk_mul_f32 v[110:111], v[60:61], v[60:61]
	v_pk_mul_f32 v[112:113], v[58:59], v[58:59]
	v_pk_add_f32 v[108:109], v[108:109], v[108:109] op_sel:[0,1] op_sel_hi:[1,0]
	v_pk_mov_b32 v[114:115], v[112:113], v[110:111] op_sel:[1,0]
	v_mov_b32_e32 v113, v111
	v_pk_add_f32 v[110:111], v[114:115], v[112:113]
	v_mul_f32_e32 v112, v51, v51
	v_pk_add_f32 v[110:111], v[110:111], v[110:111] op_sel:[0,1] op_sel_hi:[1,0]
	v_mov_b32_e32 v109, v107
	v_mov_b32_e32 v111, v112
	v_pk_add_f32 v[108:109], v[108:109], v[110:111]
	v_mul_f32_e32 v110, v55, v55
	v_mul_f32_e32 v113, v52, v52
	v_pk_fma_f32 v[110:111], v[54:55], v[54:55], v[110:111] op_sel_hi:[1,1,0]
	v_mul_f32_e32 v112, v57, v57
	v_mul_f32_e32 v114, v53, v53
	v_mov_b32_e32 v111, v113
	v_pk_fma_f32 v[112:113], v[56:57], v[56:57], v[112:113] op_sel_hi:[1,1,0]
	s_nop 0
	v_mov_b32_e32 v113, v114
	v_pk_add_f32 v[110:111], v[110:111], v[112:113]
	s_nop 0
	v_pk_add_f32 v[108:109], v[108:109], v[110:111]
	s_nop 0
	v_add_f32_e32 v107, v108, v109
	s_nop 1
	v_add_f32_dpp v107, v107, v107 quad_perm:[1,0,3,2] row_mask:0xf bank_mask:0xf
	s_nop 1
	v_add_f32_dpp v107, v107, v107 quad_perm:[2,3,0,1] row_mask:0xf bank_mask:0xf
	s_nop 1
	v_add_f32_dpp v107, v107, v107 row_half_mirror row_mask:0xf bank_mask:0xf
	s_nop 1
	v_add_f32_dpp v107, v107, v107 row_mirror row_mask:0xf bank_mask:0xf
	s_nop 1
	v_add_f32_dpp v107, v107, v107 row_bcast:15 row_mask:0xa bank_mask:0xf
	s_nop 1
	v_add_f32_dpp v107, v107, v107 row_bcast:31 row_mask:0xc bank_mask:0xf
	s_nop 0
	v_readlane_b32 s98, v107, 63
	s_nop 1
	v_mov_b32_e32 v107, s98
	v_fmamk_f32 v107, v107, 0x3a800000, v92
	s_and_saveexec_b64 s[10:11], s[0:1]
	s_cbranch_execz .Lxn_f68
	v_mul_f32_e32 v108, 0x4f800000, v107
	v_cmp_gt_f32_e32 vcc, s25, v107
	s_nop 1
	v_cndmask_b32_e32 v108, v107, v108, vcc
	v_sqrt_f32_e32 v109, v108
	s_nop 0
	v_add_u32_e32 v110, -1, v109
	v_fma_f32 v112, -v110, v109, v108
	v_add_u32_e32 v111, 1, v109
	v_cmp_ge_f32_e64 s[8:9], 0, v112
	s_nop 1
	v_cndmask_b32_e64 v110, v109, v110, s[8:9]
	v_fma_f32 v109, -v111, v109, v108
	v_cmp_lt_f32_e64 s[8:9], 0, v109
	s_nop 1
	v_cndmask_b32_e64 v109, v110, v111, s[8:9]
	v_mul_f32_e32 v110, 0x37800000, v109
	v_cndmask_b32_e32 v109, v109, v110, vcc
	v_cmp_class_f32_e32 vcc, v108, v93
	s_nop 1
	v_cndmask_b32_e32 v110, v109, v108, vcc
	v_lshl_add_u64 v[108:109], v[88:89], 2, s[16:17]
	global_store_dword v[108:109], v110, off offset:4
.Lxn_f68:
	s_or_b64 exec, exec, s[10:11]
	v_pk_mul_f32 v[108:109], v[48:49], v[48:49]
	v_pk_mul_f32 v[110:111], v[46:47], v[46:47]
	s_nop 0
	v_pk_mov_b32 v[112:113], v[110:111], v[108:109] op_sel:[1,0]
	v_mov_b32_e32 v111, v109
	v_pk_add_f32 v[108:109], v[112:113], v[110:111]
	v_pk_mul_f32 v[110:111], v[44:45], v[44:45]
	v_pk_mul_f32 v[112:113], v[42:43], v[42:43]
	v_pk_add_f32 v[108:109], v[108:109], v[108:109] op_sel:[0,1] op_sel_hi:[1,0]
	v_pk_mov_b32 v[114:115], v[112:113], v[110:111] op_sel:[1,0]
	v_mov_b32_e32 v113, v111
	v_pk_add_f32 v[110:111], v[114:115], v[112:113]
	v_mul_f32_e32 v112, v34, v34
	v_mul_f32_e32 v113, v35, v35
	v_pk_add_f32 v[110:111], v[110:111], v[110:111] op_sel:[0,1] op_sel_hi:[1,0]
	v_mov_b32_e32 v109, v112
	v_mov_b32_e32 v111, v113
	v_pk_add_f32 v[108:109], v[108:109], v[110:111]
	v_mul_f32_e32 v110, v39, v39
	v_mul_f32_e32 v112, v41, v41
	v_mul_f32_e32 v114, v36, v36
	v_mul_f32_e32 v115, v37, v37
	v_pk_fma_f32 v[110:111], v[38:39], v[38:39], v[110:111] op_sel_hi:[1,1,0]
	v_pk_fma_f32 v[112:113], v[40:41], v[40:41], v[112:113] op_sel_hi:[1,1,0]
	v_mov_b32_e32 v111, v114
	v_mov_b32_e32 v113, v115
	v_pk_add_f32 v[110:111], v[110:111], v[112:113]
	s_nop 0
	v_pk_add_f32 v[108:109], v[108:109], v[110:111]
	s_nop 0
	v_add_f32_e32 v108, v108, v109
	s_nop 1
	v_add_f32_dpp v108, v108, v108 quad_perm:[1,0,3,2] row_mask:0xf bank_mask:0xf
	s_nop 1
	v_add_f32_dpp v108, v108, v108 quad_perm:[2,3,0,1] row_mask:0xf bank_mask:0xf
	s_nop 1
	v_add_f32_dpp v108, v108, v108 row_half_mirror row_mask:0xf bank_mask:0xf
	s_nop 1
	v_add_f32_dpp v108, v108, v108 row_mirror row_mask:0xf bank_mask:0xf
	s_nop 1
	v_add_f32_dpp v108, v108, v108 row_bcast:15 row_mask:0xa bank_mask:0xf
	s_nop 1
	v_add_f32_dpp v108, v108, v108 row_bcast:31 row_mask:0xc bank_mask:0xf
	s_nop 0
	v_readlane_b32 s98, v108, 63
	s_nop 1
	v_mov_b32_e32 v108, s98
	v_fmamk_f32 v108, v108, 0x3a800000, v92
	s_and_saveexec_b64 s[10:11], s[0:1]
	s_cbranch_execz .Lxn_f70
	v_mul_f32_e32 v109, 0x4f800000, v108
	v_cmp_gt_f32_e32 vcc, s25, v108
	s_nop 1
	v_cndmask_b32_e32 v109, v108, v109, vcc
	v_sqrt_f32_e32 v110, v109
	s_nop 0
	v_add_u32_e32 v111, -1, v110
	v_fma_f32 v113, -v111, v110, v109
	v_add_u32_e32 v112, 1, v110
	v_cmp_ge_f32_e64 s[8:9], 0, v113
	s_nop 1
	v_cndmask_b32_e64 v111, v110, v111, s[8:9]
	v_fma_f32 v110, -v112, v110, v109
	v_cmp_lt_f32_e64 s[8:9], 0, v110
	s_nop 1
	v_cndmask_b32_e64 v110, v111, v112, s[8:9]
	v_mul_f32_e32 v111, 0x37800000, v110
	v_cndmask_b32_e32 v110, v110, v111, vcc
	v_cmp_class_f32_e32 vcc, v109, v93
	s_nop 1
	v_cndmask_b32_e32 v109, v110, v109, vcc
	v_lshl_add_u64 v[110:111], v[88:89], 2, s[16:17]
	global_store_dword v[110:111], v109, off offset:8
.Lxn_f70:
	s_or_b64 exec, exec, s[10:11]
	v_pk_mul_f32 v[110:111], v[32:33], v[32:33]
	v_pk_mul_f32 v[112:113], v[30:31], v[30:31]
	v_mul_f32_e32 v109, v18, v18
	v_pk_mov_b32 v[114:115], v[112:113], v[110:111] op_sel:[1,0]
	v_mov_b32_e32 v113, v111
	v_pk_add_f32 v[110:111], v[114:115], v[112:113]
	v_pk_mul_f32 v[112:113], v[28:29], v[28:29]
	v_pk_mul_f32 v[114:115], v[26:27], v[26:27]
	v_pk_add_f32 v[110:111], v[110:111], v[110:111] op_sel:[0,1] op_sel_hi:[1,0]
	v_pk_mov_b32 v[116:117], v[114:115], v[112:113] op_sel:[1,0]
	v_mov_b32_e32 v115, v113
	v_pk_add_f32 v[112:113], v[116:117], v[114:115]
	v_mul_f32_e32 v114, v19, v19
	v_pk_add_f32 v[112:113], v[112:113], v[112:113] op_sel:[0,1] op_sel_hi:[1,0]
	v_mov_b32_e32 v111, v109
	v_mov_b32_e32 v113, v114
	v_pk_add_f32 v[110:111], v[110:111], v[112:113]
	v_mul_f32_e32 v112, v23, v23
	v_mul_f32_e32 v115, v20, v20
	v_pk_fma_f32 v[112:113], v[22:23], v[22:23], v[112:113] op_sel_hi:[1,1,0]
	v_mul_f32_e32 v114, v25, v25
	v_mul_f32_e32 v116, v21, v21
	v_mov_b32_e32 v113, v115
	v_pk_fma_f32 v[114:115], v[24:25], v[24:25], v[114:115] op_sel_hi:[1,1,0]
	s_nop 0
	v_mov_b32_e32 v115, v116
	v_pk_add_f32 v[112:113], v[112:113], v[114:115]
	s_nop 0
	v_pk_add_f32 v[110:111], v[110:111], v[112:113]
	s_nop 0
	v_add_f32_e32 v109, v110, v111
	s_nop 1
	v_add_f32_dpp v109, v109, v109 quad_perm:[1,0,3,2] row_mask:0xf bank_mask:0xf
	s_nop 1
	v_add_f32_dpp v109, v109, v109 quad_perm:[2,3,0,1] row_mask:0xf bank_mask:0xf
	s_nop 1
	v_add_f32_dpp v109, v109, v109 row_half_mirror row_mask:0xf bank_mask:0xf
	s_nop 1
	v_add_f32_dpp v109, v109, v109 row_mirror row_mask:0xf bank_mask:0xf
	s_nop 1
	v_add_f32_dpp v109, v109, v109 row_bcast:15 row_mask:0xa bank_mask:0xf
	s_nop 1
	v_add_f32_dpp v109, v109, v109 row_bcast:31 row_mask:0xc bank_mask:0xf
	s_nop 0
	v_readlane_b32 s98, v109, 63
	s_nop 1
	s_and_saveexec_b64 s[8:9], s[6:7]
	s_xor_b64 s[8:9], exec, s[8:9]
	s_or_saveexec_b64 s[10:11], s[8:9]
	v_mov_b32_e32 v90, s98
	v_fmamk_f32 v90, v90, 0x3a800000, v92
	s_xor_b64 exec, exec, s[10:11]
	s_cbranch_execz .Lxn_f72
	v_mul_f32_e32 v103, 0x4f800000, v90
	v_cmp_gt_f32_e32 vcc, s25, v90
	s_nop 1
	v_cndmask_b32_e32 v103, v90, v103, vcc
	v_sqrt_f32_e32 v104, v103
	s_nop 0
	v_add_u32_e32 v105, -1, v104
	v_fma_f32 v109, -v105, v104, v103
	v_add_u32_e32 v106, 1, v104
	v_cmp_ge_f32_e64 s[8:9], 0, v109
	s_nop 1
	v_cndmask_b32_e64 v105, v104, v105, s[8:9]
	v_fma_f32 v104, -v106, v104, v103
	v_cmp_lt_f32_e64 s[8:9], 0, v104
	s_nop 1
	v_cndmask_b32_e64 v104, v105, v106, s[8:9]
	v_mul_f32_e32 v105, 0x37800000, v104
	v_cndmask_b32_e32 v104, v104, v105, vcc
	v_cmp_class_f32_e32 vcc, v103, v93
	s_nop 1
	v_cndmask_b32_e32 v103, v104, v103, vcc
	v_lshl_add_u64 v[104:105], v[88:89], 2, s[16:17]
	global_store_dword v[104:105], v103, off offset:12
.Lxn_f72:
	s_or_b64 exec, exec, s[10:11]
	v_mul_f32_e32 v103, 0x4b800000, v90
	v_cmp_gt_f32_e32 vcc, s26, v90
	v_cmp_gt_f32_e64 s[8:9], s26, v108
	v_mul_f32_e32 v105, 0x4b800000, v107
	v_cndmask_b32_e32 v90, v90, v103, vcc
	v_rsq_f32_e32 v90, v90
	v_mul_f32_e32 v103, 0x4b800000, v108
	v_cndmask_b32_e64 v103, v108, v103, s[8:9]
	v_rsq_f32_e32 v103, v103
	v_mul_f32_e32 v104, 0x45800000, v90
	v_cndmask_b32_e32 v90, v90, v104, vcc
	v_cmp_gt_f32_e32 vcc, s26, v107
	v_mul_f32_e32 v106, 0x4b800000, v102
	v_cmp_gt_f32_e64 s[10:11], s26, v102
	v_cndmask_b32_e32 v105, v107, v105, vcc
	v_rsq_f32_e32 v105, v105
	v_cndmask_b32_e64 v102, v102, v106, s[10:11]
	v_rsq_f32_e32 v106, v102
	v_mul_f32_e32 v104, 0x45800000, v103
	v_cndmask_b32_e64 v102, v103, v104, s[8:9]
	v_mul_f32_e32 v103, 0x45800000, v105
	v_cndmask_b32_e32 v104, v105, v103, vcc
	v_mul_f32_e32 v103, 0x45800000, v106
	v_cndmask_b32_e64 v106, v106, v103, s[10:11]
	v_pk_mul_f32 v[78:79], v[78:79], v[106:107] op_sel_hi:[1,0]
	v_pk_mul_f32 v[74:75], v[74:75], v[106:107] op_sel_hi:[1,0]
	v_pk_mul_f32 v[76:77], v[76:77], v[106:107] op_sel_hi:[1,0]
	v_pk_mul_f32 v[72:73], v[72:73], v[106:107] op_sel_hi:[1,0]
	v_pk_mul_f32 v[66:67], v[66:67], v[106:107] op_sel_hi:[1,0]
	v_pk_mul_f32 v[80:81], v[80:81], v[106:107] op_sel_hi:[1,0]
	v_pk_mul_f32 v[78:79], v[2:3], v[78:79]
	v_pk_mul_f32 v[76:77], v[8:9], v[76:77]
	v_pk_mul_f32 v[74:75], v[6:7], v[74:75]
	v_pk_mul_f32 v[70:71], v[70:71], v[106:107] op_sel_hi:[1,0]
	v_pk_mul_f32 v[72:73], v[12:13], v[72:73]
	v_pk_mul_f32 v[66:67], v[14:15], v[66:67]
	v_pk_mul_f32 v[80:81], v[4:5], v[80:81]
	v_cvt_pk_bf16_f32 v78, v78, v79
	v_pk_mul_f32 v[70:71], v[10:11], v[70:71]
	v_cvt_pk_bf16_f32 v79, v80, v81
	v_cvt_pk_bf16_f32 v74, v74, v75
	v_cvt_pk_bf16_f32 v75, v76, v77
	v_pk_mul_f32 v[68:69], v[68:69], v[106:107] op_sel_hi:[1,0]
	v_cvt_pk_bf16_f32 v76, v70, v71
	v_cvt_pk_bf16_f32 v72, v72, v73
	v_cvt_pk_bf16_f32 v73, v66, v67
	v_cndmask_b32_e64 v66, v78, v74, s[4:5]
	v_cndmask_b32_e64 v67, v79, v75, s[4:5]
	s_nop 1
	v_mov_b32_dpp v66, v66 quad_perm:[1,0,3,2] row_mask:0xf bank_mask:0xf
	s_nop 1
	v_mov_b32_dpp v67, v67 quad_perm:[1,0,3,2] row_mask:0xf bank_mask:0xf
	v_pk_mul_f32 v[68:69], v[16:17], v[68:69]
	v_lshlrev_b64 v[70:71], 11, v[88:89]
	v_cvt_pk_bf16_f32 v77, v68, v69
	s_waitcnt lgkmcnt(1)
	v_cndmask_b32_e64 v68, v74, v66, s[4:5]
	s_waitcnt lgkmcnt(0)
	v_cndmask_b32_e64 v69, v75, v67, s[4:5]
	v_cndmask_b32_e64 v74, v76, v73, s[4:5]
	v_cndmask_b32_e64 v75, v72, v77, s[4:5]
	s_nop 1
	v_mov_b32_dpp v74, v74 quad_perm:[1,0,3,2] row_mask:0xf bank_mask:0xf
	s_nop 1
	v_mov_b32_dpp v75, v75 quad_perm:[1,0,3,2] row_mask:0xf bank_mask:0xf
	v_cndmask_b32_e64 v66, v66, v78, s[4:5]
	v_cndmask_b32_e64 v67, v67, v79, s[4:5]
	v_lshl_add_u64 v[70:71], v[86:87], 0, v[70:71]
	v_pk_mul_f32 v[62:63], v[62:63], v[104:105] op_sel_hi:[1,0]
	v_pk_mul_f32 v[58:59], v[58:59], v[104:105] op_sel_hi:[1,0]
	v_pk_mul_f32 v[60:61], v[60:61], v[104:105] op_sel_hi:[1,0]
	v_pk_mul_f32 v[56:57], v[56:57], v[104:105] op_sel_hi:[1,0]
	v_pk_mul_f32 v[50:51], v[50:51], v[104:105] op_sel_hi:[1,0]
	global_store_dwordx4 v[70:71], v[66:69], off
	v_pk_mul_f32 v[64:65], v[64:65], v[104:105] op_sel_hi:[1,0]
	v_pk_mul_f32 v[62:63], v[2:3], v[62:63]
	s_waitcnt lgkmcnt(1)
	v_cndmask_b32_e64 v68, v73, v74, s[4:5]
	v_cndmask_b32_e64 v66, v74, v76, s[4:5]
	s_waitcnt lgkmcnt(0)
	v_cndmask_b32_e64 v69, v77, v75, s[4:5]
	v_cndmask_b32_e64 v67, v75, v72, s[4:5]
	v_pk_mul_f32 v[60:61], v[8:9], v[60:61]
	v_pk_mul_f32 v[58:59], v[6:7], v[58:59]
	v_pk_mul_f32 v[54:55], v[54:55], v[104:105] op_sel_hi:[1,0]
	v_pk_mul_f32 v[56:57], v[12:13], v[56:57]
	v_pk_mul_f32 v[52:53], v[52:53], v[104:105] op_sel_hi:[1,0]
	v_pk_mul_f32 v[50:51], v[14:15], v[50:51]
	global_store_dwordx4 v[70:71], v[66:69], off offset:1024
	v_pk_mul_f32 v[64:65], v[4:5], v[64:65]
	v_cvt_pk_bf16_f32 v62, v62, v63
	v_pk_mul_f32 v[54:55], v[10:11], v[54:55]
	v_cvt_pk_bf16_f32 v63, v64, v65
	v_cvt_pk_bf16_f32 v58, v58, v59
	v_cvt_pk_bf16_f32 v59, v60, v61
	v_pk_mul_f32 v[52:53], v[16:17], v[52:53]
	v_cvt_pk_bf16_f32 v60, v54, v55
	v_cvt_pk_bf16_f32 v56, v56, v57
	v_cvt_pk_bf16_f32 v57, v50, v51
	v_cndmask_b32_e64 v51, v62, v58, s[4:5]
	v_cvt_pk_bf16_f32 v61, v52, v53
	s_nop 1
	v_mov_b32_dpp v53, v51 quad_perm:[1,0,3,2] row_mask:0xf bank_mask:0xf
	v_cndmask_b32_e64 v51, v63, v59, s[4:5]
	s_nop 1
	v_mov_b32_dpp v64, v51 quad_perm:[1,0,3,2] row_mask:0xf bank_mask:0xf
	v_add_u32_e32 v50, 1, v88
	v_ashrrev_i32_e32 v51, 31, v50
	v_lshlrev_b64 v[54:55], 11, v[50:51]
	s_waitcnt lgkmcnt(1)
	v_cndmask_b32_e64 v52, v58, v53, s[4:5]
	v_cndmask_b32_e64 v50, v53, v62, s[4:5]
	s_waitcnt lgkmcnt(0)
	v_cndmask_b32_e64 v53, v59, v64, s[4:5]
	v_cndmask_b32_e64 v58, v60, v57, s[4:5]
	v_cndmask_b32_e64 v59, v56, v61, s[4:5]
	s_nop 1
	v_mov_b32_dpp v58, v58 quad_perm:[1,0,3,2] row_mask:0xf bank_mask:0xf
	s_nop 1
	v_mov_b32_dpp v59, v59 quad_perm:[1,0,3,2] row_mask:0xf bank_mask:0xf
	v_cndmask_b32_e64 v51, v64, v63, s[4:5]
	v_lshl_add_u64 v[54:55], v[86:87], 0, v[54:55]
	v_pk_mul_f32 v[46:47], v[46:47], v[102:103] op_sel_hi:[1,0]
	v_pk_mul_f32 v[42:43], v[42:43], v[102:103] op_sel_hi:[1,0]
	v_pk_mul_f32 v[44:45], v[44:45], v[102:103] op_sel_hi:[1,0]
	v_pk_mul_f32 v[40:41], v[40:41], v[102:103] op_sel_hi:[1,0]
	v_pk_mul_f32 v[34:35], v[34:35], v[102:103] op_sel_hi:[1,0]
	global_store_dwordx4 v[54:55], v[50:53], off
	v_pk_mul_f32 v[48:49], v[48:49], v[102:103] op_sel_hi:[1,0]
	v_pk_mul_f32 v[46:47], v[2:3], v[46:47]
	s_waitcnt lgkmcnt(1)
	v_cndmask_b32_e64 v52, v57, v58, s[4:5]
	v_cndmask_b32_e64 v50, v58, v60, s[4:5]
	s_waitcnt lgkmcnt(0)
	v_cndmask_b32_e64 v53, v61, v59, s[4:5]
	v_cndmask_b32_e64 v51, v59, v56, s[4:5]
	v_pk_mul_f32 v[44:45], v[8:9], v[44:45]
	v_pk_mul_f32 v[42:43], v[6:7], v[42:43]
	v_pk_mul_f32 v[38:39], v[38:39], v[102:103] op_sel_hi:[1,0]
	v_pk_mul_f32 v[40:41], v[12:13], v[40:41]
	v_pk_mul_f32 v[36:37], v[36:37], v[102:103] op_sel_hi:[1,0]
	v_pk_mul_f32 v[34:35], v[14:15], v[34:35]
	global_store_dwordx4 v[54:55], v[50:53], off offset:1024
	v_pk_mul_f32 v[48:49], v[4:5], v[48:49]
	v_cvt_pk_bf16_f32 v46, v46, v47
	v_pk_mul_f32 v[38:39], v[10:11], v[38:39]
	v_cvt_pk_bf16_f32 v47, v48, v49
	v_cvt_pk_bf16_f32 v42, v42, v43
	v_cvt_pk_bf16_f32 v43, v44, v45
	v_pk_mul_f32 v[36:37], v[16:17], v[36:37]
	v_cvt_pk_bf16_f32 v44, v38, v39
	v_cvt_pk_bf16_f32 v40, v40, v41
	v_cvt_pk_bf16_f32 v41, v34, v35
	v_cndmask_b32_e64 v35, v46, v42, s[4:5]
	v_cvt_pk_bf16_f32 v45, v36, v37
	s_nop 1
	v_mov_b32_dpp v37, v35 quad_perm:[1,0,3,2] row_mask:0xf bank_mask:0xf
	v_cndmask_b32_e64 v35, v47, v43, s[4:5]
	s_nop 1
	v_mov_b32_dpp v48, v35 quad_perm:[1,0,3,2] row_mask:0xf bank_mask:0xf
	v_add_u32_e32 v34, 2, v88
	v_ashrrev_i32_e32 v35, 31, v34
	v_lshlrev_b64 v[38:39], 11, v[34:35]
	s_waitcnt lgkmcnt(1)
	v_cndmask_b32_e64 v36, v42, v37, s[4:5]
	v_cndmask_b32_e64 v34, v37, v46, s[4:5]
	s_waitcnt lgkmcnt(0)
	v_cndmask_b32_e64 v37, v43, v48, s[4:5]
	v_cndmask_b32_e64 v42, v44, v41, s[4:5]
	v_cndmask_b32_e64 v43, v40, v45, s[4:5]
	s_nop 1
	v_mov_b32_dpp v42, v42 quad_perm:[1,0,3,2] row_mask:0xf bank_mask:0xf
	s_nop 1
	v_mov_b32_dpp v43, v43 quad_perm:[1,0,3,2] row_mask:0xf bank_mask:0xf
	v_cndmask_b32_e64 v35, v48, v47, s[4:5]
	v_lshl_add_u64 v[38:39], v[86:87], 0, v[38:39]
	v_pk_mul_f32 v[30:31], v[30:31], v[90:91] op_sel_hi:[1,0]
	v_pk_mul_f32 v[26:27], v[26:27], v[90:91] op_sel_hi:[1,0]
	v_pk_mul_f32 v[28:29], v[28:29], v[90:91] op_sel_hi:[1,0]
	v_pk_mul_f32 v[24:25], v[24:25], v[90:91] op_sel_hi:[1,0]
	v_pk_mul_f32 v[18:19], v[18:19], v[90:91] op_sel_hi:[1,0]
	global_store_dwordx4 v[38:39], v[34:37], off
	v_pk_mul_f32 v[32:33], v[32:33], v[90:91] op_sel_hi:[1,0]
	v_pk_mul_f32 v[30:31], v[2:3], v[30:31]
	s_waitcnt lgkmcnt(1)
	v_cndmask_b32_e64 v36, v41, v42, s[4:5]
	v_cndmask_b32_e64 v34, v42, v44, s[4:5]
	s_waitcnt lgkmcnt(0)
	v_cndmask_b32_e64 v37, v45, v43, s[4:5]
	v_cndmask_b32_e64 v35, v43, v40, s[4:5]
	v_pk_mul_f32 v[28:29], v[8:9], v[28:29]
	v_pk_mul_f32 v[26:27], v[6:7], v[26:27]
	v_pk_mul_f32 v[22:23], v[22:23], v[90:91] op_sel_hi:[1,0]
	v_pk_mul_f32 v[24:25], v[12:13], v[24:25]
	v_pk_mul_f32 v[20:21], v[20:21], v[90:91] op_sel_hi:[1,0]
	v_pk_mul_f32 v[18:19], v[14:15], v[18:19]
	global_store_dwordx4 v[38:39], v[34:37], off offset:1024
	v_pk_mul_f32 v[32:33], v[4:5], v[32:33]
	v_cvt_pk_bf16_f32 v30, v30, v31
	v_pk_mul_f32 v[22:23], v[10:11], v[22:23]
	v_cvt_pk_bf16_f32 v31, v32, v33
	v_cvt_pk_bf16_f32 v26, v26, v27
	v_cvt_pk_bf16_f32 v27, v28, v29
	v_pk_mul_f32 v[20:21], v[16:17], v[20:21]
	v_cvt_pk_bf16_f32 v28, v22, v23
	v_cvt_pk_bf16_f32 v24, v24, v25
	v_cvt_pk_bf16_f32 v25, v18, v19
	v_cndmask_b32_e64 v19, v30, v26, s[4:5]
	v_cvt_pk_bf16_f32 v29, v20, v21
	s_nop 1
	v_mov_b32_dpp v21, v19 quad_perm:[1,0,3,2] row_mask:0xf bank_mask:0xf
	v_cndmask_b32_e64 v19, v31, v27, s[4:5]
	s_nop 1
	v_mov_b32_dpp v32, v19 quad_perm:[1,0,3,2] row_mask:0xf bank_mask:0xf
	v_add_u32_e32 v18, 3, v88
	v_ashrrev_i32_e32 v19, 31, v18
	v_lshlrev_b64 v[22:23], 11, v[18:19]
	s_waitcnt lgkmcnt(1)
	v_cndmask_b32_e64 v20, v26, v21, s[4:5]
	v_cndmask_b32_e64 v18, v21, v30, s[4:5]
	s_waitcnt lgkmcnt(0)
	v_cndmask_b32_e64 v21, v27, v32, s[4:5]
	v_cndmask_b32_e64 v26, v28, v25, s[4:5]
	v_cndmask_b32_e64 v27, v24, v29, s[4:5]
	s_nop 1
	v_mov_b32_dpp v26, v26 quad_perm:[1,0,3,2] row_mask:0xf bank_mask:0xf
	s_nop 1
	v_mov_b32_dpp v27, v27 quad_perm:[1,0,3,2] row_mask:0xf bank_mask:0xf
	v_cndmask_b32_e64 v19, v32, v31, s[4:5]
	v_lshl_add_u64 v[22:23], v[86:87], 0, v[22:23]
	global_store_dwordx4 v[22:23], v[18:21], off
	s_waitcnt lgkmcnt(1)
	s_nop 0
	v_cndmask_b32_e64 v20, v25, v26, s[4:5]
	v_cndmask_b32_e64 v18, v26, v28, s[4:5]
	s_waitcnt lgkmcnt(0)
	v_cndmask_b32_e64 v21, v29, v27, s[4:5]
	v_cndmask_b32_e64 v19, v27, v24, s[4:5]
	global_store_dwordx4 v[22:23], v[18:21], off offset:1024
	v_add_u32_e32 v88, s3, v88
	s_add_u32 s99, s99, 1
	s_cmp_lt_u32 s99, 8
	s_cbranch_scc1 .Lxn_floop
	v_lshl_add_u32 v91, s92, 3, v91
	v_cmp_lt_i32_e32 vcc, s27, v91
	s_or_b64 s[18:19], vcc, s[18:19]
	s_andn2_b64 exec, exec, s[18:19]
	s_cbranch_execz .LBB0_75
.Lxn_slow:
	s_branch .LBB0_55
.LBB0_54:
	s_or_b64 exec, exec, s[8:9]
	v_add_u32_e32 v91, s92, v91
	v_cmp_lt_i32_e32 vcc, s27, v91
	s_or_b64 s[18:19], vcc, s[18:19]
	v_add_u32_e32 v88, s3, v88
	s_andn2_b64 exec, exec, s[18:19]
	s_cbranch_execz .LBB0_75
